# dt_raw skinny-MFMA phase hand-rewritten with batched double-buffered loads (was one load round trip per MFMA)
# speedup vs baseline: 1.0407x; 1.0010x over previous
; #define PHASE_IDS() const int tid = opaque_tid(), lane = tid & 63, r16 = lane & 15, q4 = lane >> 4; (void)r16; (void)q4; (void)tid
; DI f32x4 mfma16(bf16x8 a, bf16x8 b, f32x4 c) { return __builtin_amdgcn_mfma_f32_16x16x32_bf16(a, b, c, 0, 0, 0); }
; DI float row_rstd(const float* ssq, unsigned row) { return rstd4(*(const f32x4*)(ssq + row * 4u)); }
; __global__ void __launch_bounds__(512, 2) fwd_megakernel(Args args) {
;     ...
;                 PHASE_IDS();
;                 const float* ssq_in = ssq + (size_t)(3 * layer + 1) * MTOK * 4;
;                 const bf16* wdt = Wl + WL_IN / 2 + (size_t)(2560 + r16) * DM + q4 * 8;
;                 for (int rb = gw; rb < MTOK / 16; rb += NGW) {
;                     const bf16* xa = xb + (size_t)(rb * 16 + r16) * DM + q4 * 8;
;                     f32x4 acc = (f32x4){0.f, 0.f, 0.f, 0.f};
; #pragma unroll 16
;                     for (int ks = 0; ks < 32; ++ks) acc = mfma16(*(const bf16x8*)(xa + ks * 32), *(const bf16x8*)(wdt + ks * 32), acc);
;                     if (r16 < 8) {
; #pragma unroll
;                         for (int j = 0; j < 4; ++j) { const unsigned row = rb * 16 + q4 * 4 + j; dtraw[row * 8u + r16] = acc[j] * row_rstd(ssq_in, row); }
;                     }
;                 }
.LBB0_342:
	v_readlane_b32 s2, v252, 0
	v_readlane_b32 s3, v251, 0
	s_lshl_b32 s3, s3, 3
	s_add_i32 s3, s3, s2
	s_lshl_b32 s2, s3, 15
	s_add_u32 s4, s80, 0x6000000
	s_addc_u32 s5, s81, 0
	s_add_u32 s4, s4, s2
	s_addc_u32 s5, s5, 0
	v_readlane_b32 s6, v255, 29
	v_readlane_b32 s7, v255, 30
	s_sub_u32 s6, s6, 0x200
	s_subb_u32 s7, s7, 0
	v_readlane_b32 s8, v253, 58
	s_mul_i32 s8, s8, 0x30000
	s_add_u32 s8, s8, 0x5980000
	s_lshl_b32 s2, s3, 8
	s_add_u32 s2, s2, s8
	s_add_u32 s8, s80, s2
	s_addc_u32 s9, s81, 0
	s_lshl_b32 s2, s3, 9
	s_add_u32 s10, s80, 0x500000
	s_addc_u32 s11, s81, 0
	s_add_u32 s10, s10, s2
	s_addc_u32 s11, s11, 0
	v_and_b32_e32 v20, 15, v195
	v_bfe_u32 v21, v195, 4, 2
	v_lshlrev_b32_e32 v22, 11, v20
	v_lshl_add_u32 v22, v21, 4, v22
	v_lshlrev_b32_e32 v23, 6, v21
	v_lshlrev_b32_e32 v24, 7, v21
	v_lshl_add_u32 v24, v20, 2, v24
	global_load_dwordx4 v[0:3], v23, s[8:9] offset:0
	global_load_dwordx4 v[4:7], v23, s[8:9] offset:16
	global_load_dwordx4 v[8:11], v23, s[8:9] offset:32
	global_load_dwordx4 v[12:15], v23, s[8:9] offset:48
	global_load_dwordx4 v[116:119], v22, s[4:5] offset:0
	global_load_dwordx4 v[132:135], v22, s[6:7] offset:0
	global_load_dwordx4 v[120:123], v22, s[4:5] offset:64
	global_load_dwordx4 v[136:139], v22, s[6:7] offset:64
	global_load_dwordx4 v[124:127], v22, s[4:5] offset:128
	global_load_dwordx4 v[140:143], v22, s[6:7] offset:128
	global_load_dwordx4 v[128:131], v22, s[4:5] offset:192
	global_load_dwordx4 v[144:147], v22, s[6:7] offset:192
	global_load_dwordx4 v[148:151], v22, s[4:5] offset:256
	global_load_dwordx4 v[164:167], v22, s[6:7] offset:256
	global_load_dwordx4 v[152:155], v22, s[4:5] offset:320
	global_load_dwordx4 v[168:171], v22, s[6:7] offset:320
	global_load_dwordx4 v[156:159], v22, s[4:5] offset:384
	global_load_dwordx4 v[172:175], v22, s[6:7] offset:384
	global_load_dwordx4 v[160:163], v22, s[4:5] offset:448
	global_load_dwordx4 v[176:179], v22, s[6:7] offset:448
	s_waitcnt vmcnt(8)
	v_mfma_f32_16x16x32_bf16 v[16:19], v[116:119], v[132:135], 0
	v_mfma_f32_16x16x32_bf16 v[16:19], v[120:123], v[136:139], v[16:19]
	v_mfma_f32_16x16x32_bf16 v[16:19], v[124:127], v[140:143], v[16:19]
	v_mfma_f32_16x16x32_bf16 v[16:19], v[128:131], v[144:147], v[16:19]
	global_load_dwordx4 v[116:119], v22, s[4:5] offset:512
	global_load_dwordx4 v[132:135], v22, s[6:7] offset:512
	global_load_dwordx4 v[120:123], v22, s[4:5] offset:576
	global_load_dwordx4 v[136:139], v22, s[6:7] offset:576
	global_load_dwordx4 v[124:127], v22, s[4:5] offset:640
	global_load_dwordx4 v[140:143], v22, s[6:7] offset:640
	global_load_dwordx4 v[128:131], v22, s[4:5] offset:704
	global_load_dwordx4 v[144:147], v22, s[6:7] offset:704
	s_waitcnt vmcnt(8)
	v_mfma_f32_16x16x32_bf16 v[16:19], v[148:151], v[164:167], v[16:19]
	v_mfma_f32_16x16x32_bf16 v[16:19], v[152:155], v[168:171], v[16:19]
	v_mfma_f32_16x16x32_bf16 v[16:19], v[156:159], v[172:175], v[16:19]
	v_mfma_f32_16x16x32_bf16 v[16:19], v[160:163], v[176:179], v[16:19]
	global_load_dwordx4 v[148:151], v22, s[4:5] offset:768
	global_load_dwordx4 v[164:167], v22, s[6:7] offset:768
	global_load_dwordx4 v[152:155], v22, s[4:5] offset:832
	global_load_dwordx4 v[168:171], v22, s[6:7] offset:832
	global_load_dwordx4 v[156:159], v22, s[4:5] offset:896
	global_load_dwordx4 v[172:175], v22, s[6:7] offset:896
	global_load_dwordx4 v[160:163], v22, s[4:5] offset:960
	global_load_dwordx4 v[176:179], v22, s[6:7] offset:960
	s_waitcnt vmcnt(8)
	v_mfma_f32_16x16x32_bf16 v[16:19], v[116:119], v[132:135], v[16:19]
	v_mfma_f32_16x16x32_bf16 v[16:19], v[120:123], v[136:139], v[16:19]
	v_mfma_f32_16x16x32_bf16 v[16:19], v[124:127], v[140:143], v[16:19]
	v_mfma_f32_16x16x32_bf16 v[16:19], v[128:131], v[144:147], v[16:19]
	global_load_dwordx4 v[116:119], v22, s[4:5] offset:1024
	global_load_dwordx4 v[132:135], v22, s[6:7] offset:1024
	global_load_dwordx4 v[120:123], v22, s[4:5] offset:1088
	global_load_dwordx4 v[136:139], v22, s[6:7] offset:1088
	global_load_dwordx4 v[124:127], v22, s[4:5] offset:1152
	global_load_dwordx4 v[140:143], v22, s[6:7] offset:1152
	global_load_dwordx4 v[128:131], v22, s[4:5] offset:1216
	global_load_dwordx4 v[144:147], v22, s[6:7] offset:1216
	s_waitcnt vmcnt(8)
; DI f32x4 mfma16(bf16x8 a, bf16x8 b, f32x4 c) { return __builtin_amdgcn_mfma_f32_16x16x32_bf16(a, b, c, 0, 0, 0); }
; DI float row_rstd(const float* ssq, unsigned row) { return rstd4(*(const f32x4*)(ssq + row * 4u)); }
; __global__ void __launch_bounds__(512, 2) fwd_megakernel(Args args) {
;     ...
; #pragma unroll 16
;                     for (int ks = 0; ks < 32; ++ks) acc = mfma16(*(const bf16x8*)(xa + ks * 32), *(const bf16x8*)(wdt + ks * 32), acc);
;                     if (r16 < 8) {
; #pragma unroll
;                         for (int j = 0; j < 4; ++j) { const unsigned row = rb * 16 + q4 * 4 + j; dtraw[row * 8u + r16] = acc[j] * row_rstd(ssq_in, row); }
;                     }
	v_mfma_f32_16x16x32_bf16 v[16:19], v[148:151], v[164:167], v[16:19]
	v_mfma_f32_16x16x32_bf16 v[16:19], v[152:155], v[168:171], v[16:19]
	v_mfma_f32_16x16x32_bf16 v[16:19], v[156:159], v[172:175], v[16:19]
	v_mfma_f32_16x16x32_bf16 v[16:19], v[160:163], v[176:179], v[16:19]
	global_load_dwordx4 v[148:151], v22, s[4:5] offset:1280
	global_load_dwordx4 v[164:167], v22, s[6:7] offset:1280
	global_load_dwordx4 v[152:155], v22, s[4:5] offset:1344
	global_load_dwordx4 v[168:171], v22, s[6:7] offset:1344
	global_load_dwordx4 v[156:159], v22, s[4:5] offset:1408
	global_load_dwordx4 v[172:175], v22, s[6:7] offset:1408
	global_load_dwordx4 v[160:163], v22, s[4:5] offset:1472
	global_load_dwordx4 v[176:179], v22, s[6:7] offset:1472
	s_waitcnt vmcnt(8)
	v_mfma_f32_16x16x32_bf16 v[16:19], v[116:119], v[132:135], v[16:19]
	v_mfma_f32_16x16x32_bf16 v[16:19], v[120:123], v[136:139], v[16:19]
	v_mfma_f32_16x16x32_bf16 v[16:19], v[124:127], v[140:143], v[16:19]
	v_mfma_f32_16x16x32_bf16 v[16:19], v[128:131], v[144:147], v[16:19]
	global_load_dwordx4 v[116:119], v22, s[4:5] offset:1536
	global_load_dwordx4 v[132:135], v22, s[6:7] offset:1536
	global_load_dwordx4 v[120:123], v22, s[4:5] offset:1600
	global_load_dwordx4 v[136:139], v22, s[6:7] offset:1600
	global_load_dwordx4 v[124:127], v22, s[4:5] offset:1664
	global_load_dwordx4 v[140:143], v22, s[6:7] offset:1664
	global_load_dwordx4 v[128:131], v22, s[4:5] offset:1728
	global_load_dwordx4 v[144:147], v22, s[6:7] offset:1728
	s_waitcnt vmcnt(8)
	v_mfma_f32_16x16x32_bf16 v[16:19], v[148:151], v[164:167], v[16:19]
	v_mfma_f32_16x16x32_bf16 v[16:19], v[152:155], v[168:171], v[16:19]
	v_mfma_f32_16x16x32_bf16 v[16:19], v[156:159], v[172:175], v[16:19]
	v_mfma_f32_16x16x32_bf16 v[16:19], v[160:163], v[176:179], v[16:19]
	global_load_dwordx4 v[148:151], v22, s[4:5] offset:1792
	global_load_dwordx4 v[164:167], v22, s[6:7] offset:1792
	global_load_dwordx4 v[152:155], v22, s[4:5] offset:1856
	global_load_dwordx4 v[168:171], v22, s[6:7] offset:1856
	global_load_dwordx4 v[156:159], v22, s[4:5] offset:1920
	global_load_dwordx4 v[172:175], v22, s[6:7] offset:1920
	global_load_dwordx4 v[160:163], v22, s[4:5] offset:1984
	global_load_dwordx4 v[176:179], v22, s[6:7] offset:1984
	s_waitcnt vmcnt(8)
	v_mfma_f32_16x16x32_bf16 v[16:19], v[116:119], v[132:135], v[16:19]
	v_mfma_f32_16x16x32_bf16 v[16:19], v[120:123], v[136:139], v[16:19]
	v_mfma_f32_16x16x32_bf16 v[16:19], v[124:127], v[140:143], v[16:19]
	v_mfma_f32_16x16x32_bf16 v[16:19], v[128:131], v[144:147], v[16:19]
	s_waitcnt vmcnt(0)
	v_mfma_f32_16x16x32_bf16 v[16:19], v[148:151], v[164:167], v[16:19]
	v_mfma_f32_16x16x32_bf16 v[16:19], v[152:155], v[168:171], v[16:19]
	v_mfma_f32_16x16x32_bf16 v[16:19], v[156:159], v[172:175], v[16:19]
	v_mfma_f32_16x16x32_bf16 v[16:19], v[160:163], v[176:179], v[16:19]
	v_mov_b32_e32 v25, 0x358637bd
	v_cmp_gt_u32_e64 s[2:3], 8, v20
	s_nop 7
	v_add_f32_e32 v0, v0, v1
	v_add_f32_e32 v2, v2, v3
	v_add_f32_e32 v0, v0, v2
	v_fmamk_f32 v0, v0, 0x3a800000, v25
	v_rsq_f32_e32 v0, v0
	v_add_f32_e32 v4, v4, v5
	v_add_f32_e32 v6, v6, v7
	v_add_f32_e32 v4, v4, v6
	v_fmamk_f32 v4, v4, 0x3a800000, v25
	v_rsq_f32_e32 v4, v4
	v_add_f32_e32 v8, v8, v9
	v_add_f32_e32 v10, v10, v11
	v_add_f32_e32 v8, v8, v10
	v_fmamk_f32 v8, v8, 0x3a800000, v25
	v_rsq_f32_e32 v8, v8
	v_add_f32_e32 v12, v12, v13
	v_add_f32_e32 v14, v14, v15
	v_add_f32_e32 v12, v12, v14
	v_fmamk_f32 v12, v12, 0x3a800000, v25
	v_rsq_f32_e32 v12, v12
	s_nop 0
	v_mul_f32_e32 v16, v16, v0
	v_mul_f32_e32 v17, v17, v4
	v_mul_f32_e32 v18, v18, v8
	v_mul_f32_e32 v19, v19, v12
	s_mov_b64 exec, s[2:3]
	global_store_dword v24, v16, s[10:11] offset:0
	global_store_dword v24, v17, s[10:11] offset:32
	global_store_dword v24, v18, s[10:11] offset:64
	global_store_dword v24, v19, s[10:11] offset:96
	s_mov_b64 exec, -1
